# residual GEMM epilogues (Wout, Down): f32 output stores marked nt
# speedup vs baseline: 1.0037x; 1.0037x over previous
;   DI void operator()(const pg8::f32x4 (&acc)[2][2][4][2], const pg8::Unit& u, int wr, int wc, int fr, int fq) const {
;     const int row0 = u.pm * 256 + wr * 64 + fr, col0 = u.pn * 256 + wc * 32 + 8 * fq;
;     const int b = (u.pm * 256) / TT;
; #pragma unroll
;     for (int ai = 0; ai < 2; ++ai)
; #pragma unroll
;       for (int m = 0; m < 4; ++m) {
;         const int row = row0 + ai * 128 + m * 16;
;         const int t = row - b * TT;
;         const bool isc = t >= TL;
;         float* dst = isc ? xc + ((size_t)b * TC + (t - TL)) * DM : xout + ((size_t)b * TL + t) * DM;
;         const float* src = src_input ? (isc ? cin + ((size_t)b * TC + (t - TL)) * DM : xin + ((size_t)b * TL + t) * DM) : dst;
;         const float* gate = modl + (size_t)(isc ? 16 : b) * 6144 + gi * DM;
; #pragma unroll
;         for (int bj = 0; bj < 2; ++bj) {
;           const int col = col0 + bj * 128;
; #pragma unroll
;           for (int n = 0; n < 2; ++n) {
;             pg8::f32x4 sv = *(const pg8::f32x4*)(src + col + 4 * n);
;             pg8::f32x4 gv = *(const pg8::f32x4*)(gate + col + 4 * n);
;             pg8::f32x4 o = sv + gv * acc[ai][bj][m][n];
;             *(pg8::f32x4*)(dst + col + 4 * n) = o;
;           }
;         }
;       }
;   }
.LBB0_1141:
	v_lshl_or_b32 v142, s30, 8, v150
	v_mov_b32_e32 v141, s34
	v_ashrrev_i32_e32 v143, 31, v142
	v_cndmask_b32_e64 v141, v141, 16, s[8:9]
	v_mov_b64_e32 v[154:155], s[20:21]
	s_movk_i32 s8, 0x6000
	v_lshlrev_b64 v[142:143], 2, v[142:143]
	v_mad_i64_i32 v[154:155], s[8:9], v141, s8, v[154:155]
	v_lshl_add_u64 v[162:163], v[146:147], 0, v[142:143]
	v_lshl_add_u64 v[164:165], v[154:155], 0, v[142:143]
	global_load_dwordx4 v[154:157], v[162:163], off
	global_load_dwordx4 v[158:161], v[164:165], off
	v_lshl_add_u64 v[166:167], v[144:145], 0, v[142:143]
	s_movk_i32 s8, 0x800
	v_add_u32_e32 v152, 0xfffff810, v140
	v_mov_b32_e32 v141, s25
	s_and_b64 vcc, exec, s[4:5]
	s_waitcnt vmcnt(0)
	v_pk_fma_f32 v[126:127], v[126:127], v[160:161], v[156:157]
	v_pk_fma_f32 v[124:125], v[124:125], v[158:159], v[154:155]
	global_store_dwordx4 v[166:167], v[124:127], off nt
	global_load_dwordx4 v[124:127], v[162:163], off offset:16
	s_nop 0
	global_load_dwordx4 v[144:147], v[164:165], off offset:16
	s_waitcnt vmcnt(0)
	v_pk_fma_f32 v[122:123], v[122:123], v[146:147], v[126:127]
	v_pk_fma_f32 v[120:121], v[120:121], v[144:145], v[124:125]
	global_store_dwordx4 v[166:167], v[120:123], off offset:16 nt
	global_load_dwordx4 v[120:123], v[162:163], off offset:512
	s_nop 0
	global_load_dwordx4 v[124:127], v[164:165], off offset:512
	v_mov_b32_e32 v144, s48
	v_mov_b32_e32 v146, s23
	v_mov_b32_e32 v147, s35
	s_waitcnt vmcnt(0)
	v_pk_fma_f32 v[118:119], v[118:119], v[126:127], v[122:123]
	v_pk_fma_f32 v[116:117], v[116:117], v[124:125], v[120:121]
	global_store_dwordx4 v[166:167], v[116:119], off offset:512 nt
	global_load_dwordx4 v[120:123], v[162:163], off offset:528
	global_load_dwordx4 v[124:127], v[164:165], off offset:528
	v_or_b32_e32 v118, 16, v140
	v_cmp_gt_i32_e64 s[10:11], s8, v118
	s_movk_i32 s8, 0x7ff
	v_ashrrev_i32_e32 v119, 31, v118
	v_cmp_lt_i32_e64 s[8:9], s8, v118
	s_waitcnt vmcnt(0)
	v_pk_fma_f32 v[114:115], v[114:115], v[126:127], v[122:123]
	v_cndmask_b32_e64 v117, v119, 0, s[8:9]
	v_cndmask_b32_e64 v116, v118, v152, s[8:9]
	v_cndmask_b32_e64 v145, v141, v144, s[8:9]
	v_cndmask_b32_e64 v144, v146, v147, s[8:9]
	v_lshlrev_b64 v[116:117], 12, v[116:117]
	v_lshl_add_u64 v[116:117], v[144:145], 0, v[116:117]
	v_pk_fma_f32 v[112:113], v[112:113], v[124:125], v[120:121]
	global_store_dwordx4 v[166:167], v[112:115], off offset:528 nt
	s_nop 1
	v_mov_b64_e32 v[112:113], v[116:117]
	s_cbranch_vccnz .LBB0_1147
	s_and_saveexec_b64 s[50:51], s[10:11]
	s_xor_b64 s[10:11], exec, s[50:51]
	s_add_u32 s50, s12, s38
	s_addc_u32 s51, s13, s39
	v_lshlrev_b64 v[112:113], 12, v[118:119]
	v_lshl_add_u64 v[112:113], s[50:51], 0, v[112:113]
	s_andn2_saveexec_b64 s[10:11], s[10:11]
	s_add_u32 s50, s14, s36
	s_addc_u32 s51, s15, s37
	v_lshlrev_b64 v[112:113], 12, v[152:153]
	v_lshl_add_u64 v[112:113], s[50:51], 0, v[112:113]
	s_or_b64 exec, exec, s[10:11]
.LBB0_1147:
	v_mov_b32_e32 v114, s34
	v_cndmask_b32_e64 v118, v114, 16, s[8:9]
	v_mov_b64_e32 v[114:115], s[20:21]
	s_movk_i32 s8, 0x6000
	v_mad_i64_i32 v[114:115], s[8:9], v118, s8, v[114:115]
	v_lshl_add_u64 v[122:123], v[112:113], 0, v[142:143]
	v_lshl_add_u64 v[124:125], v[114:115], 0, v[142:143]
	global_load_dwordx4 v[112:115], v[122:123], off
	global_load_dwordx4 v[118:121], v[124:125], off
	v_lshl_add_u64 v[116:117], v[116:117], 0, v[142:143]
	s_movk_i32 s8, 0x800
	v_add_u32_e32 v152, 0xfffff820, v140
	s_and_b64 vcc, exec, s[4:5]
	s_waitcnt vmcnt(0)
	v_pk_fma_f32 v[110:111], v[110:111], v[120:121], v[114:115]
	v_pk_fma_f32 v[108:109], v[108:109], v[118:119], v[112:113]
	global_store_dwordx4 v[116:117], v[108:111], off nt
	global_load_dwordx4 v[108:111], v[122:123], off offset:16
	s_nop 0
	global_load_dwordx4 v[112:115], v[124:125], off offset:16
	s_waitcnt vmcnt(0)
	v_pk_fma_f32 v[106:107], v[106:107], v[114:115], v[110:111]
	v_pk_fma_f32 v[104:105], v[104:105], v[112:113], v[108:109]
	global_store_dwordx4 v[116:117], v[104:107], off offset:16 nt
	global_load_dwordx4 v[104:107], v[122:123], off offset:512
	s_nop 0
	global_load_dwordx4 v[108:111], v[124:125], off offset:512
	v_mov_b32_e32 v112, s25
	v_mov_b32_e32 v113, s48
	v_mov_b32_e32 v114, s23
	v_mov_b32_e32 v115, s35
	s_waitcnt vmcnt(0)
	v_pk_fma_f32 v[102:103], v[102:103], v[110:111], v[106:107]
	v_pk_fma_f32 v[100:101], v[100:101], v[108:109], v[104:105]
	global_store_dwordx4 v[116:117], v[100:103], off offset:512 nt
	global_load_dwordx4 v[104:107], v[122:123], off offset:528
	global_load_dwordx4 v[108:111], v[124:125], off offset:528
	v_or_b32_e32 v102, 32, v140
	v_cmp_gt_i32_e64 s[10:11], s8, v102
	s_movk_i32 s8, 0x7ff
	v_ashrrev_i32_e32 v103, 31, v102
	v_cmp_lt_i32_e64 s[8:9], s8, v102
	s_waitcnt vmcnt(0)
	v_pk_fma_f32 v[98:99], v[98:99], v[110:111], v[106:107]
	v_cndmask_b32_e64 v101, v103, 0, s[8:9]
	v_cndmask_b32_e64 v100, v102, v152, s[8:9]
	v_cndmask_b32_e64 v113, v112, v113, s[8:9]
	v_cndmask_b32_e64 v112, v114, v115, s[8:9]
	v_lshlrev_b64 v[100:101], 12, v[100:101]
	v_lshl_add_u64 v[100:101], v[112:113], 0, v[100:101]
	v_pk_fma_f32 v[96:97], v[96:97], v[108:109], v[104:105]
	global_store_dwordx4 v[116:117], v[96:99], off offset:528 nt
	s_nop 1
	v_mov_b64_e32 v[96:97], v[100:101]
	s_cbranch_vccnz .LBB0_1153
	s_and_saveexec_b64 s[50:51], s[10:11]
	s_xor_b64 s[10:11], exec, s[50:51]
	s_add_u32 s50, s12, s38
	s_addc_u32 s51, s13, s39
	v_lshlrev_b64 v[96:97], 12, v[102:103]
	v_lshl_add_u64 v[96:97], s[50:51], 0, v[96:97]
	s_andn2_saveexec_b64 s[10:11], s[10:11]
	s_add_u32 s50, s14, s36
	s_addc_u32 s51, s15, s37
	v_lshlrev_b64 v[96:97], 12, v[152:153]
	v_lshl_add_u64 v[96:97], s[50:51], 0, v[96:97]
	s_or_b64 exec, exec, s[10:11]
;   DI void operator()(const pg8::f32x4 (&acc)[2][2][4][2], const pg8::Unit& u, int wr, int wc, int fr, int fq) const {
;     const int row0 = u.pm * 256 + wr * 64 + fr, col0 = u.pn * 256 + wc * 32 + 8 * fq;
;     const int b = (u.pm * 256) / TT;
; #pragma unroll
;     for (int ai = 0; ai < 2; ++ai)
; #pragma unroll
;       for (int m = 0; m < 4; ++m) {
;         const int row = row0 + ai * 128 + m * 16;
;         const int t = row - b * TT;
;         const bool isc = t >= TL;
;         float* dst = isc ? xc + ((size_t)b * TC + (t - TL)) * DM : xout + ((size_t)b * TL + t) * DM;
;         const float* src = src_input ? (isc ? cin + ((size_t)b * TC + (t - TL)) * DM : xin + ((size_t)b * TL + t) * DM) : dst;
;         const float* gate = modl + (size_t)(isc ? 16 : b) * 6144 + gi * DM;
; #pragma unroll
;         for (int bj = 0; bj < 2; ++bj) {
;           const int col = col0 + bj * 128;
; #pragma unroll
;           for (int n = 0; n < 2; ++n) {
;             pg8::f32x4 sv = *(const pg8::f32x4*)(src + col + 4 * n);
;             pg8::f32x4 gv = *(const pg8::f32x4*)(gate + col + 4 * n);
;             pg8::f32x4 o = sv + gv * acc[ai][bj][m][n];
;             *(pg8::f32x4*)(dst + col + 4 * n) = o;
;           }
;         }
;       }
;   }
.LBB0_1153:
	v_mov_b32_e32 v98, s34
	v_cndmask_b32_e64 v102, v98, 16, s[8:9]
	v_mov_b64_e32 v[98:99], s[20:21]
	s_movk_i32 s8, 0x6000
	v_mad_i64_i32 v[98:99], s[8:9], v102, s8, v[98:99]
	v_lshl_add_u64 v[106:107], v[96:97], 0, v[142:143]
	v_lshl_add_u64 v[108:109], v[98:99], 0, v[142:143]
	global_load_dwordx4 v[96:99], v[106:107], off
	global_load_dwordx4 v[102:105], v[108:109], off
	v_lshl_add_u64 v[100:101], v[100:101], 0, v[142:143]
	s_movk_i32 s8, 0x800
	v_add_u32_e32 v152, 0xfffff830, v140
	s_and_b64 vcc, exec, s[4:5]
	s_waitcnt vmcnt(0)
	v_pk_fma_f32 v[94:95], v[94:95], v[104:105], v[98:99]
	v_pk_fma_f32 v[92:93], v[92:93], v[102:103], v[96:97]
	global_store_dwordx4 v[100:101], v[92:95], off nt
	global_load_dwordx4 v[92:95], v[106:107], off offset:16
	s_nop 0
	global_load_dwordx4 v[96:99], v[108:109], off offset:16
	s_waitcnt vmcnt(0)
	v_pk_fma_f32 v[90:91], v[90:91], v[98:99], v[94:95]
	v_pk_fma_f32 v[88:89], v[88:89], v[96:97], v[92:93]
	global_store_dwordx4 v[100:101], v[88:91], off offset:16 nt
	global_load_dwordx4 v[88:91], v[106:107], off offset:512
	s_nop 0
	global_load_dwordx4 v[92:95], v[108:109], off offset:512
	v_mov_b32_e32 v96, s25
	v_mov_b32_e32 v97, s48
	v_mov_b32_e32 v98, s23
	v_mov_b32_e32 v99, s35
	s_waitcnt vmcnt(0)
	v_pk_fma_f32 v[86:87], v[86:87], v[94:95], v[90:91]
	v_pk_fma_f32 v[84:85], v[84:85], v[92:93], v[88:89]
	global_store_dwordx4 v[100:101], v[84:87], off offset:512 nt
	global_load_dwordx4 v[88:91], v[106:107], off offset:528
	global_load_dwordx4 v[92:95], v[108:109], off offset:528
	v_or_b32_e32 v86, 48, v140
	v_cmp_gt_i32_e64 s[10:11], s8, v86
	s_movk_i32 s8, 0x7ff
	v_ashrrev_i32_e32 v87, 31, v86
	v_cmp_lt_i32_e64 s[8:9], s8, v86
	s_waitcnt vmcnt(0)
	v_pk_fma_f32 v[82:83], v[82:83], v[94:95], v[90:91]
	v_cndmask_b32_e64 v85, v87, 0, s[8:9]
	v_cndmask_b32_e64 v84, v86, v152, s[8:9]
	v_cndmask_b32_e64 v97, v96, v97, s[8:9]
	v_cndmask_b32_e64 v96, v98, v99, s[8:9]
	v_lshlrev_b64 v[84:85], 12, v[84:85]
	v_lshl_add_u64 v[84:85], v[96:97], 0, v[84:85]
	v_pk_fma_f32 v[80:81], v[80:81], v[92:93], v[88:89]
	global_store_dwordx4 v[100:101], v[80:83], off offset:528 nt
	s_nop 1
	v_mov_b64_e32 v[80:81], v[84:85]
	s_cbranch_vccnz .LBB0_1159
	s_and_saveexec_b64 s[50:51], s[10:11]
	s_xor_b64 s[10:11], exec, s[50:51]
	s_add_u32 s50, s12, s38
	s_addc_u32 s51, s13, s39
	v_lshlrev_b64 v[80:81], 12, v[86:87]
	v_lshl_add_u64 v[80:81], s[50:51], 0, v[80:81]
	s_andn2_saveexec_b64 s[10:11], s[10:11]
	s_add_u32 s50, s14, s36
	s_addc_u32 s51, s15, s37
	v_lshlrev_b64 v[80:81], 12, v[152:153]
	v_lshl_add_u64 v[80:81], s[50:51], 0, v[80:81]
	s_or_b64 exec, exec, s[10:11]
.LBB0_1159:
	v_mov_b32_e32 v82, s34
	v_cndmask_b32_e64 v86, v82, 16, s[8:9]
	v_mov_b64_e32 v[82:83], s[20:21]
	s_movk_i32 s8, 0x6000
	v_mad_i64_i32 v[82:83], s[8:9], v86, s8, v[82:83]
	v_lshl_add_u64 v[90:91], v[80:81], 0, v[142:143]
	v_lshl_add_u64 v[92:93], v[82:83], 0, v[142:143]
	global_load_dwordx4 v[80:83], v[90:91], off
	global_load_dwordx4 v[86:89], v[92:93], off
	v_lshl_add_u64 v[84:85], v[84:85], 0, v[142:143]
	s_movk_i32 s8, 0x800
	v_add_u32_e32 v152, 0xfffff880, v140
	s_and_b64 vcc, exec, s[4:5]
	s_waitcnt vmcnt(0)
	v_pk_fma_f32 v[78:79], v[78:79], v[88:89], v[82:83]
	v_pk_fma_f32 v[76:77], v[76:77], v[86:87], v[80:81]
	global_store_dwordx4 v[84:85], v[76:79], off nt
	global_load_dwordx4 v[76:79], v[90:91], off offset:16
	s_nop 0
	global_load_dwordx4 v[80:83], v[92:93], off offset:16
	s_waitcnt vmcnt(0)
	v_pk_fma_f32 v[74:75], v[74:75], v[82:83], v[78:79]
	v_pk_fma_f32 v[72:73], v[72:73], v[80:81], v[76:77]
	global_store_dwordx4 v[84:85], v[72:75], off offset:16 nt
	global_load_dwordx4 v[72:75], v[90:91], off offset:512
	s_nop 0
	global_load_dwordx4 v[76:79], v[92:93], off offset:512
	v_mov_b32_e32 v80, s25
	v_mov_b32_e32 v81, s48
	v_mov_b32_e32 v82, s23
	v_mov_b32_e32 v83, s35
	s_waitcnt vmcnt(0)
	v_pk_fma_f32 v[70:71], v[70:71], v[78:79], v[74:75]
	v_pk_fma_f32 v[68:69], v[68:69], v[76:77], v[72:73]
	global_store_dwordx4 v[84:85], v[68:71], off offset:512 nt
	global_load_dwordx4 v[72:75], v[90:91], off offset:528
	global_load_dwordx4 v[76:79], v[92:93], off offset:528
	v_add_u32_e32 v70, 0x80, v140
	v_cmp_gt_i32_e64 s[10:11], s8, v70
	s_movk_i32 s8, 0x7ff
	v_ashrrev_i32_e32 v71, 31, v70
	v_cmp_lt_i32_e64 s[8:9], s8, v70
	s_waitcnt vmcnt(0)
	v_pk_fma_f32 v[66:67], v[66:67], v[78:79], v[74:75]
	v_cndmask_b32_e64 v69, v71, 0, s[8:9]
	v_cndmask_b32_e64 v68, v70, v152, s[8:9]
	v_cndmask_b32_e64 v81, v80, v81, s[8:9]
	v_cndmask_b32_e64 v80, v82, v83, s[8:9]
	v_lshlrev_b64 v[68:69], 12, v[68:69]
	v_lshl_add_u64 v[68:69], v[80:81], 0, v[68:69]
	v_pk_fma_f32 v[64:65], v[64:65], v[76:77], v[72:73]
	global_store_dwordx4 v[84:85], v[64:67], off offset:528 nt
	s_nop 1
	v_mov_b64_e32 v[64:65], v[68:69]
	s_cbranch_vccnz .LBB0_1165
	s_and_saveexec_b64 s[50:51], s[10:11]
	s_xor_b64 s[10:11], exec, s[50:51]
	s_add_u32 s50, s12, s38
	s_addc_u32 s51, s13, s39
	v_lshlrev_b64 v[64:65], 12, v[70:71]
	v_lshl_add_u64 v[64:65], s[50:51], 0, v[64:65]
	s_andn2_saveexec_b64 s[10:11], s[10:11]
	s_add_u32 s50, s14, s36
	s_addc_u32 s51, s15, s37
	v_lshlrev_b64 v[64:65], 12, v[152:153]
	v_lshl_add_u64 v[64:65], s[50:51], 0, v[64:65]
	s_or_b64 exec, exec, s[10:11]
;   DI void operator()(const pg8::f32x4 (&acc)[2][2][4][2], const pg8::Unit& u, int wr, int wc, int fr, int fq) const {
;     const int row0 = u.pm * 256 + wr * 64 + fr, col0 = u.pn * 256 + wc * 32 + 8 * fq;
;     const int b = (u.pm * 256) / TT;
; #pragma unroll
;     for (int ai = 0; ai < 2; ++ai)
; #pragma unroll
;       for (int m = 0; m < 4; ++m) {
;         const int row = row0 + ai * 128 + m * 16;
;         const int t = row - b * TT;
;         const bool isc = t >= TL;
;         float* dst = isc ? xc + ((size_t)b * TC + (t - TL)) * DM : xout + ((size_t)b * TL + t) * DM;
;         const float* src = src_input ? (isc ? cin + ((size_t)b * TC + (t - TL)) * DM : xin + ((size_t)b * TL + t) * DM) : dst;
;         const float* gate = modl + (size_t)(isc ? 16 : b) * 6144 + gi * DM;
; #pragma unroll
;         for (int bj = 0; bj < 2; ++bj) {
;           const int col = col0 + bj * 128;
; #pragma unroll
;           for (int n = 0; n < 2; ++n) {
;             pg8::f32x4 sv = *(const pg8::f32x4*)(src + col + 4 * n);
;             pg8::f32x4 gv = *(const pg8::f32x4*)(gate + col + 4 * n);
;             pg8::f32x4 o = sv + gv * acc[ai][bj][m][n];
;             *(pg8::f32x4*)(dst + col + 4 * n) = o;
;           }
;         }
;       }
;   }
.LBB0_1165:
	v_mov_b32_e32 v66, s34
	v_cndmask_b32_e64 v70, v66, 16, s[8:9]
	v_mov_b64_e32 v[66:67], s[20:21]
	s_movk_i32 s8, 0x6000
	v_mad_i64_i32 v[66:67], s[8:9], v70, s8, v[66:67]
	v_lshl_add_u64 v[74:75], v[64:65], 0, v[142:143]
	v_lshl_add_u64 v[76:77], v[66:67], 0, v[142:143]
	global_load_dwordx4 v[64:67], v[74:75], off
	global_load_dwordx4 v[70:73], v[76:77], off
	v_lshl_add_u64 v[68:69], v[68:69], 0, v[142:143]
	s_movk_i32 s8, 0x800
	v_add_u32_e32 v152, 0xfffff890, v140
	s_and_b64 vcc, exec, s[4:5]
	s_waitcnt vmcnt(0)
	v_pk_fma_f32 v[62:63], v[62:63], v[72:73], v[66:67]
	v_pk_fma_f32 v[60:61], v[60:61], v[70:71], v[64:65]
	global_store_dwordx4 v[68:69], v[60:63], off nt
	global_load_dwordx4 v[60:63], v[74:75], off offset:16
	s_nop 0
	global_load_dwordx4 v[64:67], v[76:77], off offset:16
	s_waitcnt vmcnt(0)
	v_pk_fma_f32 v[58:59], v[58:59], v[66:67], v[62:63]
	v_pk_fma_f32 v[56:57], v[56:57], v[64:65], v[60:61]
	global_store_dwordx4 v[68:69], v[56:59], off offset:16 nt
	global_load_dwordx4 v[56:59], v[74:75], off offset:512
	s_nop 0
	global_load_dwordx4 v[60:63], v[76:77], off offset:512
	v_mov_b32_e32 v64, s25
	v_mov_b32_e32 v65, s48
	v_mov_b32_e32 v66, s23
	v_mov_b32_e32 v67, s35
	s_waitcnt vmcnt(0)
	v_pk_fma_f32 v[54:55], v[54:55], v[62:63], v[58:59]
	v_pk_fma_f32 v[52:53], v[52:53], v[60:61], v[56:57]
	global_store_dwordx4 v[68:69], v[52:55], off offset:512 nt
	global_load_dwordx4 v[56:59], v[74:75], off offset:528
	global_load_dwordx4 v[60:63], v[76:77], off offset:528
	v_add_u32_e32 v54, 0x90, v140
	v_cmp_gt_i32_e64 s[10:11], s8, v54
	s_movk_i32 s8, 0x7ff
	v_ashrrev_i32_e32 v55, 31, v54
	v_cmp_lt_i32_e64 s[8:9], s8, v54
	s_waitcnt vmcnt(0)
	v_pk_fma_f32 v[50:51], v[50:51], v[62:63], v[58:59]
	v_cndmask_b32_e64 v53, v55, 0, s[8:9]
	v_cndmask_b32_e64 v52, v54, v152, s[8:9]
	v_cndmask_b32_e64 v65, v64, v65, s[8:9]
	v_cndmask_b32_e64 v64, v66, v67, s[8:9]
	v_lshlrev_b64 v[52:53], 12, v[52:53]
	v_lshl_add_u64 v[52:53], v[64:65], 0, v[52:53]
	v_pk_fma_f32 v[48:49], v[48:49], v[60:61], v[56:57]
	global_store_dwordx4 v[68:69], v[48:51], off offset:528 nt
	s_nop 1
	v_mov_b64_e32 v[48:49], v[52:53]
	s_cbranch_vccnz .LBB0_1171
	s_and_saveexec_b64 s[50:51], s[10:11]
	s_xor_b64 s[10:11], exec, s[50:51]
	s_add_u32 s50, s12, s38
	s_addc_u32 s51, s13, s39
	v_lshlrev_b64 v[48:49], 12, v[54:55]
	v_lshl_add_u64 v[48:49], s[50:51], 0, v[48:49]
	s_andn2_saveexec_b64 s[10:11], s[10:11]
	s_add_u32 s50, s14, s36
	s_addc_u32 s51, s15, s37
	v_lshlrev_b64 v[48:49], 12, v[152:153]
	v_lshl_add_u64 v[48:49], s[50:51], 0, v[48:49]
	s_or_b64 exec, exec, s[10:11]
.LBB0_1171:
	v_mov_b32_e32 v50, s34
	v_cndmask_b32_e64 v54, v50, 16, s[8:9]
	v_mov_b64_e32 v[50:51], s[20:21]
	s_movk_i32 s8, 0x6000
	v_mad_i64_i32 v[50:51], s[8:9], v54, s8, v[50:51]
	v_lshl_add_u64 v[58:59], v[48:49], 0, v[142:143]
	v_lshl_add_u64 v[60:61], v[50:51], 0, v[142:143]
	global_load_dwordx4 v[48:51], v[58:59], off
	global_load_dwordx4 v[54:57], v[60:61], off
	v_lshl_add_u64 v[52:53], v[52:53], 0, v[142:143]
	s_movk_i32 s8, 0x800
	v_add_u32_e32 v152, 0xfffff8a0, v140
	s_and_b64 vcc, exec, s[4:5]
	s_waitcnt vmcnt(0)
	v_pk_fma_f32 v[46:47], v[46:47], v[56:57], v[50:51]
	v_pk_fma_f32 v[44:45], v[44:45], v[54:55], v[48:49]
	global_store_dwordx4 v[52:53], v[44:47], off nt
	global_load_dwordx4 v[44:47], v[58:59], off offset:16
	s_nop 0
	global_load_dwordx4 v[48:51], v[60:61], off offset:16
	s_waitcnt vmcnt(0)
	v_pk_fma_f32 v[42:43], v[42:43], v[50:51], v[46:47]
	v_pk_fma_f32 v[40:41], v[40:41], v[48:49], v[44:45]
	global_store_dwordx4 v[52:53], v[40:43], off offset:16 nt
	global_load_dwordx4 v[40:43], v[58:59], off offset:512
	s_nop 0
	global_load_dwordx4 v[44:47], v[60:61], off offset:512
	v_mov_b32_e32 v48, s25
	v_mov_b32_e32 v49, s48
	v_mov_b32_e32 v50, s23
	v_mov_b32_e32 v51, s35
	s_waitcnt vmcnt(0)
	v_pk_fma_f32 v[38:39], v[38:39], v[46:47], v[42:43]
	v_pk_fma_f32 v[36:37], v[36:37], v[44:45], v[40:41]
	global_store_dwordx4 v[52:53], v[36:39], off offset:512 nt
	global_load_dwordx4 v[40:43], v[58:59], off offset:528
	global_load_dwordx4 v[44:47], v[60:61], off offset:528
	v_add_u32_e32 v38, 0xa0, v140
	v_cmp_gt_i32_e64 s[10:11], s8, v38
	s_movk_i32 s8, 0x7ff
	v_ashrrev_i32_e32 v39, 31, v38
	v_cmp_lt_i32_e64 s[8:9], s8, v38
	s_waitcnt vmcnt(0)
	v_pk_fma_f32 v[34:35], v[34:35], v[46:47], v[42:43]
	v_cndmask_b32_e64 v37, v39, 0, s[8:9]
	v_cndmask_b32_e64 v36, v38, v152, s[8:9]
	v_cndmask_b32_e64 v49, v48, v49, s[8:9]
	v_cndmask_b32_e64 v48, v50, v51, s[8:9]
	v_lshlrev_b64 v[36:37], 12, v[36:37]
	v_lshl_add_u64 v[36:37], v[48:49], 0, v[36:37]
	v_pk_fma_f32 v[32:33], v[32:33], v[44:45], v[40:41]
	global_store_dwordx4 v[52:53], v[32:35], off offset:528 nt
	s_nop 1
	v_mov_b64_e32 v[32:33], v[36:37]
	s_cbranch_vccnz .LBB0_1177
	s_and_saveexec_b64 s[50:51], s[10:11]
	s_xor_b64 s[10:11], exec, s[50:51]
	s_add_u32 s50, s12, s38
	s_addc_u32 s51, s13, s39
	v_lshlrev_b64 v[32:33], 12, v[38:39]
	v_lshl_add_u64 v[32:33], s[50:51], 0, v[32:33]
	s_andn2_saveexec_b64 s[10:11], s[10:11]
	s_add_u32 s50, s14, s36
	s_addc_u32 s51, s15, s37
	v_lshlrev_b64 v[32:33], 12, v[152:153]
	v_lshl_add_u64 v[32:33], s[50:51], 0, v[32:33]
	s_or_b64 exec, exec, s[10:11]
;   DI void operator()(const pg8::f32x4 (&acc)[2][2][4][2], const pg8::Unit& u, int wr, int wc, int fr, int fq) const {
;     const int row0 = u.pm * 256 + wr * 64 + fr, col0 = u.pn * 256 + wc * 32 + 8 * fq;
;     const int b = (u.pm * 256) / TT;
; #pragma unroll
;     for (int ai = 0; ai < 2; ++ai)
; #pragma unroll
;       for (int m = 0; m < 4; ++m) {
;         const int row = row0 + ai * 128 + m * 16;
;         const int t = row - b * TT;
;         const bool isc = t >= TL;
;         float* dst = isc ? xc + ((size_t)b * TC + (t - TL)) * DM : xout + ((size_t)b * TL + t) * DM;
;         const float* src = src_input ? (isc ? cin + ((size_t)b * TC + (t - TL)) * DM : xin + ((size_t)b * TL + t) * DM) : dst;
;         const float* gate = modl + (size_t)(isc ? 16 : b) * 6144 + gi * DM;
; #pragma unroll
;         for (int bj = 0; bj < 2; ++bj) {
;           const int col = col0 + bj * 128;
; #pragma unroll
;           for (int n = 0; n < 2; ++n) {
;             pg8::f32x4 sv = *(const pg8::f32x4*)(src + col + 4 * n);
;             pg8::f32x4 gv = *(const pg8::f32x4*)(gate + col + 4 * n);
;             pg8::f32x4 o = sv + gv * acc[ai][bj][m][n];
;             *(pg8::f32x4*)(dst + col + 4 * n) = o;
;           }
;         }
;       }
;   }
.LBB0_1177:
	v_mov_b32_e32 v34, s34
	v_cndmask_b32_e64 v38, v34, 16, s[8:9]
	v_mov_b64_e32 v[34:35], s[20:21]
	s_movk_i32 s8, 0x6000
	v_mad_i64_i32 v[34:35], s[8:9], v38, s8, v[34:35]
	v_lshl_add_u64 v[42:43], v[32:33], 0, v[142:143]
	v_lshl_add_u64 v[44:45], v[34:35], 0, v[142:143]
	global_load_dwordx4 v[32:35], v[42:43], off
	global_load_dwordx4 v[38:41], v[44:45], off
	v_lshl_add_u64 v[36:37], v[36:37], 0, v[142:143]
	s_and_b64 vcc, exec, s[4:5]
	s_movk_i32 s4, 0x800
	v_add_u32_e32 v152, 0xfffff8b0, v140
	s_waitcnt vmcnt(0)
	v_pk_fma_f32 v[30:31], v[30:31], v[40:41], v[34:35]
	v_pk_fma_f32 v[28:29], v[28:29], v[38:39], v[32:33]
	global_store_dwordx4 v[36:37], v[28:31], off nt
	global_load_dwordx4 v[28:31], v[42:43], off offset:16
	s_nop 0
	global_load_dwordx4 v[32:35], v[44:45], off offset:16
	s_waitcnt vmcnt(0)
	v_pk_fma_f32 v[26:27], v[26:27], v[34:35], v[30:31]
	v_pk_fma_f32 v[24:25], v[24:25], v[32:33], v[28:29]
	global_store_dwordx4 v[36:37], v[24:27], off offset:16 nt
	global_load_dwordx4 v[24:27], v[42:43], off offset:512
	s_nop 0
	global_load_dwordx4 v[28:31], v[44:45], off offset:512
	v_mov_b32_e32 v32, s25
	v_mov_b32_e32 v33, s48
	v_mov_b32_e32 v34, s23
	v_mov_b32_e32 v35, s35
	s_waitcnt vmcnt(0)
	v_pk_fma_f32 v[22:23], v[22:23], v[30:31], v[26:27]
	v_pk_fma_f32 v[20:21], v[20:21], v[28:29], v[24:25]
	global_store_dwordx4 v[36:37], v[20:23], off offset:512 nt
	global_load_dwordx4 v[24:27], v[42:43], off offset:528
	global_load_dwordx4 v[28:31], v[44:45], off offset:528
	v_add_u32_e32 v22, 0xb0, v140
	v_cmp_gt_i32_e64 s[8:9], s4, v22
	s_movk_i32 s4, 0x7ff
	v_ashrrev_i32_e32 v23, 31, v22
	v_cmp_lt_i32_e64 s[4:5], s4, v22
	s_waitcnt vmcnt(0)
	v_pk_fma_f32 v[18:19], v[18:19], v[30:31], v[26:27]
	v_cndmask_b32_e64 v21, v23, 0, s[4:5]
	v_cndmask_b32_e64 v20, v22, v152, s[4:5]
	v_cndmask_b32_e64 v33, v32, v33, s[4:5]
	v_cndmask_b32_e64 v32, v34, v35, s[4:5]
	v_lshlrev_b64 v[20:21], 12, v[20:21]
	v_lshl_add_u64 v[20:21], v[32:33], 0, v[20:21]
	v_pk_fma_f32 v[16:17], v[16:17], v[28:29], v[24:25]
	global_store_dwordx4 v[36:37], v[16:19], off offset:528 nt
	s_nop 1
	v_mov_b64_e32 v[16:17], v[20:21]
	s_cbranch_vccnz .LBB0_1183
	s_and_saveexec_b64 s[10:11], s[8:9]
	s_xor_b64 s[8:9], exec, s[10:11]
	s_add_u32 s10, s12, s38
	s_addc_u32 s11, s13, s39
	v_lshlrev_b64 v[16:17], 12, v[22:23]
	v_lshl_add_u64 v[16:17], s[10:11], 0, v[16:17]
	s_andn2_saveexec_b64 s[8:9], s[8:9]
	s_add_u32 s10, s14, s36
	s_addc_u32 s11, s15, s37
	v_lshlrev_b64 v[16:17], 12, v[152:153]
	v_lshl_add_u64 v[16:17], s[10:11], 0, v[16:17]
	s_or_b64 exec, exec, s[8:9]
.LBB0_1183:
	v_mov_b32_e32 v18, s34
	v_cndmask_b32_e64 v22, v18, 16, s[4:5]
	v_mov_b64_e32 v[18:19], s[20:21]
	s_movk_i32 s4, 0x6000
	v_mad_i64_i32 v[18:19], s[4:5], v22, s4, v[18:19]
	v_lshl_add_u64 v[24:25], v[16:17], 0, v[142:143]
	v_lshl_add_u64 v[26:27], v[18:19], 0, v[142:143]
	v_lshl_add_u64 v[28:29], v[20:21], 0, v[142:143]
	global_load_dwordx4 v[16:19], v[24:25], off
	global_load_dwordx4 v[20:23], v[26:27], off
	s_mov_b64 s[4:5], -1
	s_andn2_b64 vcc, exec, s[2:3]
	s_waitcnt vmcnt(0)
	v_pk_fma_f32 v[14:15], v[14:15], v[22:23], v[18:19]
	v_pk_fma_f32 v[12:13], v[12:13], v[20:21], v[16:17]
	global_store_dwordx4 v[28:29], v[12:15], off nt
	global_load_dwordx4 v[12:15], v[24:25], off offset:16
	s_nop 0
	global_load_dwordx4 v[16:19], v[26:27], off offset:16
	s_waitcnt vmcnt(0)
	v_pk_fma_f32 v[10:11], v[10:11], v[18:19], v[14:15]
	v_pk_fma_f32 v[8:9], v[8:9], v[16:17], v[12:13]
	global_store_dwordx4 v[28:29], v[8:11], off offset:16 nt
	global_load_dwordx4 v[8:11], v[24:25], off offset:512
	s_nop 0
	global_load_dwordx4 v[12:15], v[26:27], off offset:512
	s_waitcnt vmcnt(0)
	v_pk_fma_f32 v[6:7], v[6:7], v[14:15], v[10:11]
	v_pk_fma_f32 v[4:5], v[4:5], v[12:13], v[8:9]
	global_store_dwordx4 v[28:29], v[4:7], off offset:512 nt
	global_load_dwordx4 v[4:7], v[24:25], off offset:528
	s_nop 0
	global_load_dwordx4 v[8:11], v[26:27], off offset:528
	s_waitcnt vmcnt(0)
	v_pk_fma_f32 v[2:3], v[2:3], v[10:11], v[6:7]
	v_pk_fma_f32 v[0:1], v[0:1], v[8:9], v[4:5]
	global_store_dwordx4 v[28:29], v[0:3], off offset:528 nt
	s_cbranch_vccnz .LBB0_1128
	s_andn2_b64 vcc, exec, s[16:17]
	s_cbranch_vccnz .LBB0_1127
	s_barrier
	s_branch .LBB0_1127

;   DI void operator()(const pg8::f32x4 (&acc)[2][2][4][2], const pg8::Unit& u, int wr, int wc, int fr, int fq) const {
;     const int row0 = u.pm * 256 + wr * 64 + fr, col0 = u.pn * 256 + wc * 32 + 8 * fq;
;     const int b = (u.pm * 256) / TT;
; #pragma unroll
;     for (int ai = 0; ai < 2; ++ai)
; #pragma unroll
;       for (int m = 0; m < 4; ++m) {
;         const int row = row0 + ai * 128 + m * 16;
;         const int t = row - b * TT;
;         const bool isc = t >= TL;
;         float* dst = isc ? xc + ((size_t)b * TC + (t - TL)) * DM : xout + ((size_t)b * TL + t) * DM;
;         const float* src = src_input ? (isc ? cin + ((size_t)b * TC + (t - TL)) * DM : xin + ((size_t)b * TL + t) * DM) : dst;
;         const float* gate = modl + (size_t)(isc ? 16 : b) * 6144 + gi * DM;
; #pragma unroll
;         for (int bj = 0; bj < 2; ++bj) {
;           const int col = col0 + bj * 128;
; #pragma unroll
;           for (int n = 0; n < 2; ++n) {
;             pg8::f32x4 sv = *(const pg8::f32x4*)(src + col + 4 * n);
;             pg8::f32x4 gv = *(const pg8::f32x4*)(gate + col + 4 * n);
;             pg8::f32x4 o = sv + gv * acc[ai][bj][m][n];
;             *(pg8::f32x4*)(dst + col + 4 * n) = o;
;           }
;         }
;       }
;   }
.LBB0_1507:
	s_mov_b32 s4, 0x38e38e39
	v_mul_hi_i32 v142, v148, s4
	v_lshrrev_b32_e32 v144, 31, v142
	v_ashrrev_i32_e32 v142, 1, v142
	v_add_u32_e32 v142, v142, v144
	s_movk_i32 s4, 0xf700
	s_load_dwordx4 s[24:27], s[0:1], 0x100
	v_lshlrev_b32_e32 v143, 8, v148
	v_mul_lo_u32 v144, v142, s4
	v_add_u32_e32 v143, v144, v143
	v_add_u32_e32 v160, v143, v154
	v_ashrrev_i32_e32 v143, 31, v142
	v_readlane_b32 s4, v252, 14
	s_movk_i32 s21, 0x7ff
	v_lshlrev_b64 v[144:145], 23, v[142:143]
	v_lshlrev_b64 v[146:147], 20, v[142:143]
	v_ashrrev_i32_e32 v143, 31, v160
	v_add_u32_e32 v148, 0xfffff800, v160
	v_readlane_b32 s5, v252, 15
	v_cmp_lt_i32_e32 vcc, s21, v160
	v_lshl_or_b32 v150, v149, 8, v156
	s_waitcnt lgkmcnt(0)
	v_lshl_add_u64 v[144:145], s[24:25], 0, v[144:145]
	v_lshl_add_u64 v[146:147], s[4:5], 0, v[146:147]
	v_cndmask_b32_e64 v149, v143, 0, vcc
	v_cndmask_b32_e32 v148, v160, v148, vcc
	v_cndmask_b32_e32 v163, v145, v147, vcc
	v_cndmask_b32_e32 v162, v144, v146, vcc
	v_lshlrev_b64 v[148:149], 12, v[148:149]
	v_lshl_add_u64 v[162:163], v[162:163], 0, v[148:149]
	v_cndmask_b32_e64 v143, v142, 16, vcc
	v_mov_b64_e32 v[148:149], s[10:11]
	s_movk_i32 s22, 0x6000
	v_ashrrev_i32_e32 v151, 31, v150
	v_mad_i64_i32 v[164:165], s[4:5], v143, s22, v[148:149]
	v_lshlrev_b64 v[150:151], 2, v[150:151]
	v_lshl_add_u64 v[176:177], v[164:165], 0, v[150:151]
	v_lshl_add_u64 v[174:175], v[162:163], 0, v[150:151]
	s_mov_b64 s[4:5], 0x10000
	s_mov_b64 s[24:25], 0x50000
	global_load_dwordx4 v[202:205], v[176:177], off
	global_load_dwordx4 v[206:209], v[176:177], off offset:16
	global_load_dwordx4 v[210:213], v[176:177], off offset:512
	global_load_dwordx4 v[214:217], v[176:177], off offset:528
	global_load_dwordx4 v[218:221], v[174:175], off
	global_load_dwordx4 v[222:225], v[174:175], off offset:16
	global_load_dwordx4 v[226:229], v[174:175], off offset:512
	global_load_dwordx4 v[230:233], v[174:175], off offset:528
	v_lshl_add_u64 v[142:143], v[174:175], 0, s[4:5]
	global_load_dwordx4 v[234:237], v[142:143], off
	global_load_dwordx4 v[238:241], v[142:143], off offset:16
	global_load_dwordx4 v[242:245], v[142:143], off offset:512
	global_load_dwordx4 v[246:249], v[142:143], off offset:528
	v_lshl_add_u64 v[144:145], v[142:143], 0, s[4:5]
	global_load_dwordx4 v[160:163], v[144:145], off
	global_load_dwordx4 v[164:167], v[144:145], off offset:16
	global_load_dwordx4 v[168:171], v[144:145], off offset:512
	global_load_dwordx4 v[178:181], v[144:145], off offset:528
	v_lshl_add_u64 v[146:147], v[144:145], 0, s[4:5]
	v_lshl_add_u64 v[148:149], v[146:147], 0, s[24:25]
	v_lshl_add_u64 v[150:151], v[148:149], 0, s[4:5]
	v_lshl_add_u64 v[192:193], v[150:151], 0, s[4:5]
	v_lshl_add_u64 v[194:195], v[192:193], 0, s[4:5]
	s_waitcnt vmcnt(8)
	v_pk_fma_f32 v[126:127], v[126:127], v[204:205], v[220:221]
	v_pk_fma_f32 v[124:125], v[124:125], v[202:203], v[218:219]
	v_pk_fma_f32 v[122:123], v[122:123], v[208:209], v[224:225]
	v_pk_fma_f32 v[120:121], v[120:121], v[206:207], v[222:223]
	v_pk_fma_f32 v[118:119], v[118:119], v[212:213], v[228:229]
	v_pk_fma_f32 v[116:117], v[116:117], v[210:211], v[226:227]
	v_pk_fma_f32 v[106:107], v[106:107], v[216:217], v[232:233]
	v_pk_fma_f32 v[104:105], v[104:105], v[214:215], v[230:231]
	global_store_dwordx4 v[174:175], v[124:127], off nt
	global_store_dwordx4 v[174:175], v[120:123], off offset:16 nt
	global_store_dwordx4 v[174:175], v[116:119], off offset:512 nt
	global_store_dwordx4 v[174:175], v[104:107], off offset:528 nt
	global_load_dwordx4 v[218:221], v[146:147], off
	global_load_dwordx4 v[222:225], v[146:147], off offset:16
	global_load_dwordx4 v[226:229], v[146:147], off offset:512
	global_load_dwordx4 v[230:233], v[146:147], off offset:528
	s_waitcnt vmcnt(12)
	v_pk_fma_f32 v[114:115], v[114:115], v[204:205], v[236:237]
	v_pk_fma_f32 v[112:113], v[112:113], v[202:203], v[234:235]
	v_pk_fma_f32 v[110:111], v[110:111], v[208:209], v[240:241]
	v_pk_fma_f32 v[108:109], v[108:109], v[206:207], v[238:239]
	v_pk_fma_f32 v[102:103], v[102:103], v[212:213], v[244:245]
	v_pk_fma_f32 v[100:101], v[100:101], v[210:211], v[242:243]
	v_pk_fma_f32 v[90:91], v[90:91], v[216:217], v[248:249]
	v_pk_fma_f32 v[88:89], v[88:89], v[214:215], v[246:247]
	global_store_dwordx4 v[142:143], v[112:115], off nt
	global_store_dwordx4 v[142:143], v[108:111], off offset:16 nt
	global_store_dwordx4 v[142:143], v[100:103], off offset:512 nt
	global_store_dwordx4 v[142:143], v[88:91], off offset:528 nt
	global_load_dwordx4 v[234:237], v[148:149], off
	global_load_dwordx4 v[238:241], v[148:149], off offset:16
	global_load_dwordx4 v[242:245], v[148:149], off offset:512
	global_load_dwordx4 v[246:249], v[148:149], off offset:528
	s_waitcnt vmcnt(16)
;   DI void operator()(const pg8::f32x4 (&acc)[2][2][4][2], const pg8::Unit& u, int wr, int wc, int fr, int fq) const {
;     const int row0 = u.pm * 256 + wr * 64 + fr, col0 = u.pn * 256 + wc * 32 + 8 * fq;
;     const int b = (u.pm * 256) / TT;
; #pragma unroll
;     for (int ai = 0; ai < 2; ++ai)
; #pragma unroll
;       for (int m = 0; m < 4; ++m) {
;         const int row = row0 + ai * 128 + m * 16;
;         const int t = row - b * TT;
;         const bool isc = t >= TL;
;         float* dst = isc ? xc + ((size_t)b * TC + (t - TL)) * DM : xout + ((size_t)b * TL + t) * DM;
;         const float* src = src_input ? (isc ? cin + ((size_t)b * TC + (t - TL)) * DM : xin + ((size_t)b * TL + t) * DM) : dst;
;         const float* gate = modl + (size_t)(isc ? 16 : b) * 6144 + gi * DM;
; #pragma unroll
;         for (int bj = 0; bj < 2; ++bj) {
;           const int col = col0 + bj * 128;
; #pragma unroll
;           for (int n = 0; n < 2; ++n) {
;             pg8::f32x4 sv = *(const pg8::f32x4*)(src + col + 4 * n);
;             pg8::f32x4 gv = *(const pg8::f32x4*)(gate + col + 4 * n);
;             pg8::f32x4 o = sv + gv * acc[ai][bj][m][n];
;             *(pg8::f32x4*)(dst + col + 4 * n) = o;
;           }
;         }
;       }
;   }
	v_pk_fma_f32 v[98:99], v[98:99], v[204:205], v[162:163]
	v_pk_fma_f32 v[96:97], v[96:97], v[202:203], v[160:161]
	v_pk_fma_f32 v[94:95], v[94:95], v[208:209], v[166:167]
	v_pk_fma_f32 v[92:93], v[92:93], v[206:207], v[164:165]
	v_pk_fma_f32 v[86:87], v[86:87], v[212:213], v[170:171]
	v_pk_fma_f32 v[84:85], v[84:85], v[210:211], v[168:169]
	v_pk_fma_f32 v[74:75], v[74:75], v[216:217], v[180:181]
	v_pk_fma_f32 v[72:73], v[72:73], v[214:215], v[178:179]
	global_store_dwordx4 v[144:145], v[96:99], off nt
	global_store_dwordx4 v[144:145], v[92:95], off offset:16 nt
	global_store_dwordx4 v[144:145], v[84:87], off offset:512 nt
	global_store_dwordx4 v[144:145], v[72:75], off offset:528 nt
	global_load_dwordx4 v[160:163], v[150:151], off
	global_load_dwordx4 v[164:167], v[150:151], off offset:16
	global_load_dwordx4 v[168:171], v[150:151], off offset:512
	global_load_dwordx4 v[178:181], v[150:151], off offset:528
	s_waitcnt vmcnt(16)
	v_pk_fma_f32 v[82:83], v[82:83], v[204:205], v[220:221]
	v_pk_fma_f32 v[80:81], v[80:81], v[202:203], v[218:219]
	v_pk_fma_f32 v[78:79], v[78:79], v[208:209], v[224:225]
	v_pk_fma_f32 v[76:77], v[76:77], v[206:207], v[222:223]
	v_pk_fma_f32 v[70:71], v[70:71], v[212:213], v[228:229]
	v_pk_fma_f32 v[68:69], v[68:69], v[210:211], v[226:227]
	v_pk_fma_f32 v[66:67], v[66:67], v[216:217], v[232:233]
	v_pk_fma_f32 v[64:65], v[64:65], v[214:215], v[230:231]
	global_store_dwordx4 v[146:147], v[80:83], off nt
	global_store_dwordx4 v[146:147], v[76:79], off offset:16 nt
	global_store_dwordx4 v[146:147], v[68:71], off offset:512 nt
	global_store_dwordx4 v[146:147], v[64:67], off offset:528 nt
	global_load_dwordx4 v[218:221], v[192:193], off
	global_load_dwordx4 v[222:225], v[192:193], off offset:16
	global_load_dwordx4 v[226:229], v[192:193], off offset:512
	global_load_dwordx4 v[230:233], v[192:193], off offset:528
	s_waitcnt vmcnt(16)
	v_pk_fma_f32 v[62:63], v[62:63], v[204:205], v[236:237]
	v_pk_fma_f32 v[60:61], v[60:61], v[202:203], v[234:235]
	v_pk_fma_f32 v[58:59], v[58:59], v[208:209], v[240:241]
	v_pk_fma_f32 v[56:57], v[56:57], v[206:207], v[238:239]
	v_pk_fma_f32 v[54:55], v[54:55], v[212:213], v[244:245]
	v_pk_fma_f32 v[52:53], v[52:53], v[210:211], v[242:243]
	v_pk_fma_f32 v[42:43], v[42:43], v[216:217], v[248:249]
	v_pk_fma_f32 v[40:41], v[40:41], v[214:215], v[246:247]
	global_store_dwordx4 v[148:149], v[60:63], off nt
	global_store_dwordx4 v[148:149], v[56:59], off offset:16 nt
	global_store_dwordx4 v[148:149], v[52:55], off offset:512 nt
	global_store_dwordx4 v[148:149], v[40:43], off offset:528 nt
	global_load_dwordx4 v[234:237], v[194:195], off
	global_load_dwordx4 v[238:241], v[194:195], off offset:16
	global_load_dwordx4 v[242:245], v[194:195], off offset:512
	global_load_dwordx4 v[246:249], v[194:195], off offset:528
	s_waitcnt vmcnt(16)
	v_pk_fma_f32 v[50:51], v[50:51], v[204:205], v[162:163]
	v_pk_fma_f32 v[48:49], v[48:49], v[202:203], v[160:161]
	v_pk_fma_f32 v[46:47], v[46:47], v[208:209], v[166:167]
	v_pk_fma_f32 v[44:45], v[44:45], v[206:207], v[164:165]
	v_pk_fma_f32 v[38:39], v[38:39], v[212:213], v[170:171]
	v_pk_fma_f32 v[36:37], v[36:37], v[210:211], v[168:169]
	v_pk_fma_f32 v[26:27], v[26:27], v[216:217], v[180:181]
	v_pk_fma_f32 v[24:25], v[24:25], v[214:215], v[178:179]
	global_store_dwordx4 v[150:151], v[48:51], off nt
	global_store_dwordx4 v[150:151], v[44:47], off offset:16 nt
	global_store_dwordx4 v[150:151], v[36:39], off offset:512 nt
	global_store_dwordx4 v[150:151], v[24:27], off offset:528 nt
	s_waitcnt vmcnt(12)
	v_pk_fma_f32 v[34:35], v[34:35], v[204:205], v[220:221]
	v_pk_fma_f32 v[32:33], v[32:33], v[202:203], v[218:219]
	v_pk_fma_f32 v[30:31], v[30:31], v[208:209], v[224:225]
	v_pk_fma_f32 v[28:29], v[28:29], v[206:207], v[222:223]
	v_pk_fma_f32 v[22:23], v[22:23], v[212:213], v[228:229]
	v_pk_fma_f32 v[20:21], v[20:21], v[210:211], v[226:227]
	v_pk_fma_f32 v[10:11], v[10:11], v[216:217], v[232:233]
	v_pk_fma_f32 v[8:9], v[8:9], v[214:215], v[230:231]
	global_store_dwordx4 v[192:193], v[32:35], off nt
	global_store_dwordx4 v[192:193], v[28:31], off offset:16 nt
	global_store_dwordx4 v[192:193], v[20:23], off offset:512 nt
	global_store_dwordx4 v[192:193], v[8:11], off offset:528 nt
	s_waitcnt vmcnt(8)
	v_pk_fma_f32 v[18:19], v[18:19], v[204:205], v[236:237]
	v_pk_fma_f32 v[16:17], v[16:17], v[202:203], v[234:235]
	v_pk_fma_f32 v[14:15], v[14:15], v[208:209], v[240:241]
	v_pk_fma_f32 v[12:13], v[12:13], v[206:207], v[238:239]
	v_pk_fma_f32 v[6:7], v[6:7], v[212:213], v[244:245]
	v_pk_fma_f32 v[4:5], v[4:5], v[210:211], v[242:243]
	v_pk_fma_f32 v[2:3], v[2:3], v[216:217], v[248:249]
	v_pk_fma_f32 v[0:1], v[0:1], v[214:215], v[246:247]
	global_store_dwordx4 v[194:195], v[16:19], off nt
	global_store_dwordx4 v[194:195], v[12:15], off offset:16 nt
	global_store_dwordx4 v[194:195], v[4:7], off offset:512 nt
	global_store_dwordx4 v[194:195], v[0:3], off offset:528 nt
	s_and_b64 vcc, exec, s[2:3]
	s_mov_b64 s[2:3], -1
	s_cbranch_vccnz .LBB0_1496
	s_andn2_b64 vcc, exec, s[6:7]
	s_cbranch_vccnz .LBB0_1495
	s_barrier
	s_branch .LBB0_1495
